# rotK tab3 + nt hint on the attention super-unit K/V LDS-DMA loads
# baseline (speedup 1.0000x reference)
; template <int MODE> ...
;     ...
;     bf16x8 qf[4];
; #pragma unroll
;     for (int d0 = 0; d0 < 4; ++d0) qf[d0] = *(const bf16x8*)(Qrow + r32 * 64 + d0 * 16 + hi * 8);
;     const int kkey = 8 * w + (lane >> 3), kch = (lane & 7) ^ ((kkey >> 1) & 7);
;     const int vkey = 8 * w + ((lane >> 2) & 7), vch = 4 * ((lane >> 5) & 1) + (lane & 3);
;     const bf16_t* kg = Kb + kkey * 64 + kch * 8;
;     const bf16_t* vg = Vb + vkey * 64 + vch * 8;
;     const unsigned ring0 = (unsigned)(unsigned long)ring;
;     const unsigned kdst = (unsigned)__builtin_amdgcn_readfirstlane(ring0 + w * 1024), vdst = kdst + 8192;
;     const float cq = (MODE == 1) ? tab[qpos0 + r32] : 0.f;
;     const float cfar = (MODE == 0) ? tab[256] : 0.f;
;     const unsigned vl = v_lane_off(lane);
;     St S; st_init(S);
;     asm volatile("" :: "v"(qf[0]), "v"(qf[1]), "v"(qf[2]), "v"(qf[3]));
;     constexpr bool REV = (MODE == 1);
;     ...
;     int s0 = 0, s1 = 16384, s2 = 32768;
;     glds16(kg + (size_t)SU_T(T0) * 4096, kdst + s0); glds16(vg + (size_t)SU_T(T0) * 4096, vdst + s0);
;     if (T0 + 1 < T1) { glds16(kg + (size_t)SU_T(T0 + 1) * 4096, kdst + s1); glds16(vg + (size_t)SU_T(T0 + 1) * 4096, vdst + s1);
;                        asm volatile("s_waitcnt vmcnt(2) lgkmcnt(0)\n\ts_barrier" ::: "memory"); }
;     else             { asm volatile("s_waitcnt vmcnt(0) lgkmcnt(0)\n\ts_barrier" ::: "memory"); }
; __device__ __forceinline__ void phase2(const Params& P, LAS unsigned char* lds, int tid, int lane, int wave) {
;     ...
;             const int mode = it < 8, u = it & 7;
;             const int hc = 8 * u + wave;
;             const size_t qrow = (size_t)b * SEQ + hc * 32;
;             const size_t ho = (size_t)(b * 8 + h) * 2048 * 64;
;             const bf16_t* Qrow = (const bf16_t*)(P.ws + WS_SEG + (size_t)(mode ? 4 : 0) * SEG_STRIDE) + ho + (size_t)hc * 32 * 64;
;             const bf16_t* Grow = (const bf16_t*)(P.ws + WS_SEG + (size_t)(mode ? 7 : 3) * SEG_STRIDE) + ho + (size_t)hc * 32 * 64;
;             const bf16_t* Kb = (const bf16_t*)(P.ws + WS_SEG + (size_t)(mode ? 5 : 1) * SEG_STRIDE) + ho;
;             const bf16_t* Vb = (const bf16_t*)(P.ws + WS_SEG + (size_t)(mode ? 6 : 2) * SEG_STRIDE) + ho;
;             bf16_t* Yrow = (bf16_t*)(P.ws + WS_H) + qrow * 1024 + (mode ? 512 : 0) + h * 64;
;             if (mode) {
.LBB0_598:
	s_and_b32 s2, s99, 7
	s_lshl_b32 s0, s2, 3
	s_add_i32 s0, s86, s0
	s_and_b32 s4, s21, 7
	s_lshr_b32 s6, s0, 1
	s_lshl_b32 s0, s4, 3
	s_add_i32 s40, s0, s86
	s_lshl_b32 s12, s40, 5
	s_cmp_lt_u32 s21, 8
	s_mov_b32 s1, 0x14a00000
	s_cselect_b32 s0, 0x10800000, 0
	s_cselect_b32 s5, s1, 0x4200000
	s_mov_b32 s1, 0x18c00000
	s_mov_b32 s41, s13
	s_cselect_b32 s3, 0x1ce00000, s33
	s_cselect_b32 s7, s1, 0x8400000
	s_cselect_b32 s10, 0x400, 0
	s_add_u32 s8, s29, s0
	s_addc_u32 s9, s98, 0
	s_lshl_b64 s[0:1], s[40:41], 12
	s_add_u32 s42, s8, s0
	s_addc_u32 s43, s9, s1
	s_add_u32 s3, s29, s3
	s_addc_u32 s9, s98, 0
	s_add_u32 s8, s3, s0
	s_addc_u32 s9, s9, s1
	s_add_u32 s36, s29, s5
	s_addc_u32 s37, s98, 0
	s_add_u32 s38, s29, s7
	s_addc_u32 s39, s98, 0
	s_lshl_b64 s[0:1], s[12:13], 11
	s_add_u32 s0, s11, s0
	s_addc_u32 s1, s19, s1
	s_add_u32 s0, s0, s10
	s_addc_u32 s1, s1, 0
	v_readlane_b32 s16, v240, 45
	v_readlane_b32 s17, v240, 46
	s_add_u32 s16, s0, s16
	s_addc_u32 s17, s1, s17
	s_cmp_gt_u32 s21, 7
	s_mov_b64 s[0:1], -1
	s_cbranch_scc0 .LBB0_634
	v_mov_b32_e32 v143, v120
	v_mov_b32_e32 v5, v1
	v_and_b32_e32 v144, 31, v143
	v_bfe_u32 v6, v143, 5, 1
	v_lshlrev_b32_e32 v0, 7, v144
	v_lshl_add_u64 v[2:3], s[42:43], 0, v[0:1]
	v_lshlrev_b32_e32 v4, 4, v6
	v_lshl_add_u64 v[2:3], v[2:3], 0, v[4:5]
	global_load_dwordx4 v[80:83], v[2:3], off
	global_load_dwordx4 v[84:87], v[2:3], off offset:32
	global_load_dwordx4 v[88:91], v[2:3], off offset:64
	global_load_dwordx4 v[92:95], v[2:3], off offset:96
	s_lshl_b32 s3, s4, 2
	s_add_i32 s0, s3, -8
	s_cmp_gt_u32 s4, 1
	v_readfirstlane_b32 s4, v143
	v_and_b32_e32 v2, 32, v143
	v_lshlrev_b32_e32 v4, 3, v143
	s_cselect_b32 s44, s0, 0
	s_ashr_i32 s7, s4, 6
	v_bfe_u32 v142, v143, 3, 3
	v_and_or_b32 v2, v4, 24, v2
	s_lshl_b32 s4, s7, 3
	v_lshlrev_b32_e32 v4, 1, v2
	v_or_b32_e32 v2, s4, v142
	v_lshrrev_b32_e32 v7, 2, v143
	v_lshrrev_b32_e32 v11, 1, v2
	v_and_or_b32 v9, v7, 7, s4
	v_lshlrev_b32_e32 v8, 6, v2
	v_xor_b32_e32 v2, v11, v143
	v_lshlrev_b32_e32 v10, 6, v9
	v_ashrrev_i32_e32 v9, 31, v8
	v_lshlrev_b32_e32 v2, 4, v2
	v_mov_b32_e32 v3, v1
	s_lshl_b32 s5, s7, 10
	v_ashrrev_i32_e32 v11, 31, v10
	v_lshl_add_u64 v[8:9], v[8:9], 1, s[36:37]
	v_and_b32_e32 v2, 0x70, v2
	s_mov_b32 s1, s13
	ds_read_b32 v145, v1 offset:17664
	s_lshl_b32 s0, s44, 13
	s_add_i32 s4, s5, 0
	v_lshl_add_u64 v[10:11], v[10:11], 1, s[38:39]
	v_lshl_add_u64 v[2:3], v[8:9], 0, v[2:3]
	s_add_i32 s24, s4, 0x4800
	v_lshl_add_u64 v[4:5], v[10:11], 0, v[4:5]
	v_lshl_add_u64 v[8:9], v[2:3], 0, s[0:1]
	s_add_i32 s25, s4, 0x6800
	s_add_i32 s15, s3, 4
	s_mov_b32 s5, m0
	s_mov_b32 m0, s24
	s_nop 0
	global_load_lds_dwordx4 v[8:9], off nt
	s_mov_b32 m0, s5
	v_lshl_add_u64 v[8:9], v[4:5], 0, s[0:1]
	s_mov_b32 s0, m0
	s_mov_b32 m0, s25
	s_nop 0
	global_load_lds_dwordx4 v[8:9], off nt
	s_mov_b32 m0, s0
	s_or_b32 s5, s44, 1
	s_cmp_ge_u32 s5, s15
	s_mov_b64 s[0:1], -1
	s_cbranch_scc0 .LBB0_601
	s_waitcnt vmcnt(0) lgkmcnt(0)
	s_barrier
	s_cbranch_execnz .LBB0_603
	s_branch .LBB0_602

; template <int MODE> ...
;     ...
;     glds16(kg + (size_t)SU_T(T0) * 4096, kdst + s0); glds16(vg + (size_t)SU_T(T0) * 4096, vdst + s0);
;     if (T0 + 1 < T1) { glds16(kg + (size_t)SU_T(T0 + 1) * 4096, kdst + s1); glds16(vg + (size_t)SU_T(T0 + 1) * 4096, vdst + s1);
;                        asm volatile("s_waitcnt vmcnt(2) lgkmcnt(0)\n\ts_barrier" ::: "memory"); }
;     else             { asm volatile("s_waitcnt vmcnt(0) lgkmcnt(0)\n\ts_barrier" ::: "memory"); }
.LBB0_602:
	s_lshl_b32 s0, s5, 13
	s_mov_b32 s1, s13
	v_lshl_add_u64 v[8:9], v[2:3], 0, s[0:1]
	s_add_i32 s5, s4, 0x8800
	s_mov_b32 s10, m0
	s_mov_b32 m0, s5
	s_nop 0
	global_load_lds_dwordx4 v[8:9], off nt
	s_mov_b32 m0, s10
	v_lshl_add_u64 v[8:9], v[4:5], 0, s[0:1]
	s_add_i32 s4, s4, 0xa800
	s_mov_b32 s0, m0
	s_mov_b32 m0, s4
	s_nop 0
	global_load_lds_dwordx4 v[8:9], off nt
	s_mov_b32 m0, s0
	s_waitcnt vmcnt(2) lgkmcnt(0)
	s_barrier

; template <int MODE> ...
;     ...
;         const bool more = (s + 2 < T1);
;         if (more) { glds16(kg + (size_t)SU_T(s + 2) * 4096, kdst + s2); glds16(vg + (size_t)SU_T(s + 2) * 4096, vdst + s2); }
.Lk0_noK:
	s_add_i32 s0, s44, 2
	s_cmp_ge_u32 s0, s15
	s_cselect_b64 s[46:47], -1, 0
	s_and_b64 vcc, exec, s[46:47]
	s_cbranch_vccnz .Lk0_nodma
	s_add_i32 s1, s49, s24
	s_mov_b32 s2, m0
	s_mov_b32 m0, s1
	s_nop 0
	global_load_lds_dwordx4 v[124:125], off nt
	s_add_i32 s0, s49, s25
	s_mov_b32 m0, s0
	s_nop 0
	global_load_lds_dwordx4 v[122:123], off nt
	s_mov_b32 m0, s2

; __device__ __forceinline__ int crow(int r, int hi) { return (r & 3) + 8 * (r >> 2) + 4 * hi; }
; __device__ __forceinline__ unsigned v_lane_off(int lane) { return (unsigned)((4 * (lane >> 5) + ((lane & 15) >> 2)) * 64 + ((lane >> 4) & 1) * 32 + (lane & 3) * 8); }
; template <int MODE>
; __device__ __forceinline__ void step64(St& S, const bf16x8 (&qf)[4], int t, int qpos0, bool diag, bool first, float cq, float cfar, const LAS float* tab,
;                                        const LAS unsigned char* buf, unsigned vaddr, int r32, int hi) {
;     ...
;         const int qrel = qpos0 - t * 64 + r32;
; #pragma unroll
;         for (int r = 0; r < 16; ++r) { if (crow(r, hi) > qrel) sa[r] = -1e30f; if (crow(r, hi) + 32 > qrel) sb[r] = -1e30f; }
; template <int MODE> ...
;     asm volatile("" : "+v"(tid)); lane = tid & 63;
;     const int r32 = lane & 31, hi = lane >> 5;
;     const int w = __builtin_amdgcn_readfirstlane(tid >> 6);
;     bf16x8 qf[4];
; #pragma unroll
;     for (int d0 = 0; d0 < 4; ++d0) qf[d0] = *(const bf16x8*)(Qrow + r32 * 64 + d0 * 16 + hi * 8);
;     const int kkey = 8 * w + (lane >> 3), kch = (lane & 7) ^ ((kkey >> 1) & 7);
;     const int vkey = 8 * w + ((lane >> 2) & 7), vch = 4 * ((lane >> 5) & 1) + (lane & 3);
;     const bf16_t* kg = Kb + kkey * 64 + kch * 8;
;     const bf16_t* vg = Vb + vkey * 64 + vch * 8;
;     const unsigned ring0 = (unsigned)(unsigned long)ring;
;     const unsigned kdst = (unsigned)__builtin_amdgcn_readfirstlane(ring0 + w * 1024), vdst = kdst + 8192;
;     const float cq = (MODE == 1) ? tab[qpos0 + r32] : 0.f;
;     const float cfar = (MODE == 0) ? tab[256] : 0.f;
;     const unsigned vl = v_lane_off(lane);
;     St S; st_init(S);
;     asm volatile("" :: "v"(qf[0]), "v"(qf[1]), "v"(qf[2]), "v"(qf[3]));
;     constexpr bool REV = (MODE == 1);
;     ...
;     int s0 = 0, s1 = 16384, s2 = 32768;
;     glds16(kg + (size_t)SU_T(T0) * 4096, kdst + s0); glds16(vg + (size_t)SU_T(T0) * 4096, vdst + s0);
;     if (T0 + 1 < T1) { glds16(kg + (size_t)SU_T(T0 + 1) * 4096, kdst + s1); glds16(vg + (size_t)SU_T(T0 + 1) * 4096, vdst + s1);
;                        asm volatile("s_waitcnt vmcnt(2) lgkmcnt(0)\n\ts_barrier" ::: "memory"); }
;     else             { asm volatile("s_waitcnt vmcnt(0) lgkmcnt(0)\n\ts_barrier" ::: "memory"); }
.LBB0_634:
	s_and_b64 vcc, exec, s[0:1]
	s_cbranch_vccz .LBB0_597
	v_mov_b32_e32 v123, v120
	v_mov_b32_e32 v5, v1
	v_and_b32_e32 v124, 31, v123
	v_bfe_u32 v6, v123, 5, 1
	v_lshlrev_b32_e32 v0, 7, v124
	v_lshl_add_u64 v[2:3], s[42:43], 0, v[0:1]
	v_lshlrev_b32_e32 v4, 4, v6
	v_lshl_add_u64 v[2:3], v[2:3], 0, v[4:5]
	global_load_dwordx4 v[80:83], v[2:3], off
	global_load_dwordx4 v[84:87], v[2:3], off offset:32
	global_load_dwordx4 v[88:91], v[2:3], off offset:64
	global_load_dwordx4 v[92:95], v[2:3], off offset:96
	s_lshl_b32 s4, s21, 14
	s_lshl_b32 s1, s12, 2
	s_mov_b32 s3, s13
	s_or_b32 s2, s4, 0x3000
	v_readfirstlane_b32 s10, v123
	s_sub_i32 s15, 0, s6
	s_add_i32 s1, s1, 0
	v_lshrrev_b32_e32 v8, 3, v123
	v_bfe_u32 v9, v123, 2, 2
	v_lshlrev_b32_e32 v10, 1, v123
	s_lshl_b64 s[6:7], s[2:3], 1
	v_lshrrev_b32_e32 v125, 1, v123
	s_ashr_i32 s2, s10, 6
	v_bfe_u32 v122, v123, 3, 3
	v_lshlrev_b32_e32 v5, 3, v123
	v_lshl_add_u32 v12, v124, 2, s1
	v_and_or_b32 v8, v8, 4, v9
	v_and_b32_e32 v9, 32, v10
	v_bitop3_b32 v10, v6, v125, 7 bitop3:0x78
	s_lshl_b32 s1, s2, 3
	v_lshrrev_b32_e32 v2, 2, v123
	v_bfe_u32 v11, v123, 1, 3
	v_and_b32_e32 v5, 24, v5
	v_lshlrev_b32_e32 v8, 6, v8
	v_lshl_or_b32 v143, v10, 4, v0
	v_or_b32_e32 v10, s1, v122
	v_bitop3_b32 v13, v6, v11, 2 bitop3:0x36
	v_bitop3_b32 v14, v6, v11, 4 bitop3:0x36
	v_bitop3_b32 v11, v6, v11, 6 bitop3:0x36
	v_lshlrev_b32_e32 v16, 2, v6
	v_and_or_b32 v6, v123, 32, v5
	v_and_or_b32 v2, v2, 7, s1
	v_or3_b32 v147, v5, v9, v8
	v_lshrrev_b32_e32 v5, 1, v10
	v_lshlrev_b32_e32 v8, 6, v10
	v_lshlrev_b32_e32 v10, 6, v2
	v_xor_b32_e32 v2, v5, v123
	v_lshl_or_b32 v146, v11, 4, v0
	v_ashrrev_i32_e32 v9, 31, v8
	v_ashrrev_i32_e32 v11, 31, v10
	v_lshlrev_b32_e32 v2, 4, v2
	v_mov_b32_e32 v3, v1
	v_mov_b32_e32 v7, v1
	s_mov_b32 s5, s13
	s_bitset1_b32 s4, 13
	s_lshl_b32 s3, s2, 10
	v_lshlrev_b32_e32 v6, 1, v6
	v_lshl_add_u64 v[8:9], v[8:9], 1, s[36:37]
	v_lshl_add_u64 v[10:11], v[10:11], 1, s[38:39]
	v_and_b32_e32 v2, 0x70, v2
	s_lshl_b64 s[4:5], s[4:5], 1
	s_add_i32 s1, s3, 0
	v_lshl_add_u64 v[6:7], v[10:11], 0, v[6:7]
	v_lshl_add_u64 v[2:3], v[8:9], 0, v[2:3]
	ds_read_b32 v142, v12
	v_lshl_or_b32 v144, v13, 4, v0
	v_lshl_or_b32 v145, v14, 4, v0
	s_add_i32 s20, s1, 0x4800
	v_lshl_add_u64 v[10:11], v[6:7], 0, s[4:5]
	v_lshl_add_u64 v[12:13], v[2:3], 0, s[6:7]
	v_lshl_add_u64 v[14:15], v[2:3], 0, s[4:5]
	s_add_i32 s3, s1, 0x6800
	v_lshl_add_u64 v[8:9], v[6:7], 0, s[6:7]
	s_lshr_b32 s28, s40, 1
	s_add_i32 s10, s1, 0x8800
	s_add_i32 s1, s1, 0xa800
	v_or_b32_e32 v0, 32, v16
	v_or_b32_e32 v17, 33, v16
	v_or_b32_e32 v5, 2, v16
	v_or_b32_e32 v18, 42, v16
	v_or_b32_e32 v19, 11, v16
	v_or_b32_e32 v20, 43, v16
	v_or_b32_e32 v21, 16, v16
	v_or_b32_e32 v22, 48, v16
	v_or_b32_e32 v23, 17, v16
	s_mov_b32 s4, m0
	s_mov_b32 m0, s20
	s_nop 0
	global_load_lds_dwordx4 v[12:13], off nt
	s_mov_b32 m0, s4
	v_or_b32_e32 v12, 40, v16
	s_mov_b32 s4, m0
	s_mov_b32 m0, s3
	s_nop 0
	global_load_lds_dwordx4 v[8:9], off nt
	s_mov_b32 m0, s4
	v_or_b32_e32 v8, 34, v16
	s_mov_b32 s4, m0
	s_mov_b32 m0, s10
	s_nop 0
	global_load_lds_dwordx4 v[14:15], off nt
	s_mov_b32 m0, s4
	v_or_b32_e32 v14, 41, v16
	s_mov_b32 s4, m0
	s_mov_b32 m0, s1
	s_nop 0
	global_load_lds_dwordx4 v[10:11], off nt
	s_mov_b32 m0, s4
	s_lshl_b32 s1, s28, 6
	s_sub_i32 s1, s12, s1
	v_or_b32_e32 v15, 10, v16
	v_or_b32_e32 v37, s1, v124
	s_waitcnt vmcnt(2) lgkmcnt(0)
	s_barrier
	v_or_b32_e32 v9, 3, v16
	v_or_b32_e32 v10, 35, v16
	v_or_b32_e32 v11, 8, v16
	v_or_b32_e32 v13, 9, v16
	v_or_b32_e32 v24, 49, v16
	v_or_b32_e32 v25, 18, v16
	v_or_b32_e32 v26, 50, v16
	v_or_b32_e32 v27, 19, v16
	v_or_b32_e32 v28, 51, v16
	v_or_b32_e32 v29, 24, v16
	v_or_b32_e32 v30, 56, v16
	v_or_b32_e32 v31, 25, v16
	v_or_b32_e32 v32, 57, v16
	v_or_b32_e32 v33, 26, v16
	v_or_b32_e32 v34, 58, v16
	v_or_b32_e32 v35, 27, v16
	v_or_b32_e32 v36, 59, v16
	v_cmp_gt_i32_e64 s[56:57], v14, v37
	v_cmp_gt_i32_e64 s[58:59], v15, v37
	v_mov_b32_e32 v14, v1
	v_mov_b32_e32 v15, v1
	s_mov_b32 s23, s86
	s_lshl_b32 s33, s21, 2
	v_cmp_gt_i32_e64 s[34:35], v16, v37
	v_cmp_gt_i32_e64 s[36:37], v0, v37
	v_cmp_lt_i32_e64 s[38:39], v16, v37
	v_cmp_gt_i32_e64 s[40:41], v17, v37
	v_cmp_gt_i32_e64 s[42:43], v5, v37
	v_cmp_gt_i32_e64 s[44:45], v8, v37
	v_cmp_gt_i32_e64 s[46:47], v9, v37
	v_cmp_gt_i32_e64 s[48:49], v10, v37
	v_cmp_gt_i32_e64 s[50:51], v11, v37
	v_cmp_gt_i32_e64 s[52:53], v12, v37
	v_cmp_gt_i32_e64 s[54:55], v13, v37
	v_cmp_gt_i32_e64 s[60:61], v18, v37
	v_cmp_gt_i32_e64 s[62:63], v19, v37
	v_cmp_gt_i32_e64 s[64:65], v20, v37
	v_cmp_gt_i32_e64 s[66:67], v21, v37
	v_cmp_gt_i32_e64 s[68:69], v22, v37
	v_cmp_gt_i32_e64 s[70:71], v23, v37
	v_cmp_gt_i32_e64 s[72:73], v24, v37
	v_cmp_gt_i32_e64 s[74:75], v25, v37
	v_cmp_gt_i32_e64 s[76:77], v26, v37
	v_cmp_gt_i32_e64 s[78:79], v27, v37
	v_cmp_gt_i32_e64 s[80:81], v28, v37
	v_cmp_gt_i32_e64 s[82:83], v29, v37
	v_cmp_gt_i32_e64 s[84:85], v30, v37
	v_cmp_gt_i32_e64 s[86:87], v31, v37
	v_cmp_gt_i32_e64 s[88:89], v32, v37
	v_cmp_gt_i32_e64 s[90:91], v33, v37
	v_cmp_gt_i32_e64 s[92:93], v34, v37
	v_cmp_gt_i32_e64 s[94:95], v35, v37
	v_cmp_gt_i32_e64 s[96:97], v36, v37
	v_lshl_add_u64 v[116:117], v[6:7], 0, s[30:31]
	v_lshl_add_u64 v[118:119], v[2:3], 0, s[30:31]
	v_add_u32_e32 v148, s14, v4
	v_mov_b32_e32 v0, v1
	v_mov_b32_e32 v2, v1
	v_mov_b32_e32 v3, v1
	v_mov_b32_e32 v4, v1
	v_mov_b32_e32 v5, v1
	v_mov_b32_e32 v6, v1
	v_mov_b32_e32 v7, v1
	v_mov_b32_e32 v8, v1
	v_mov_b32_e32 v9, v1
	v_mov_b32_e32 v10, v1
	v_mov_b32_e32 v11, v1
	v_mov_b32_e32 v12, v1
	v_mov_b32_e32 v13, v1
	v_mov_b64_e32 v[30:31], v[14:15]
	v_mov_b64_e32 v[46:47], v[14:15]
	s_mov_b32 s0, 0
	s_mov_b32 s19, 2
	s_add_i32 s33, s33, 4
	v_mov_b32_e32 v150, 0
	s_mov_b32 s12, 0x8000
	s_movk_i32 s10, 0x4000
	s_mov_b32 s1, s18
	v_mov_b32_e32 v149, 0
	v_mov_b64_e32 v[28:29], v[12:13]
	v_mov_b64_e32 v[26:27], v[10:11]
	v_mov_b64_e32 v[24:25], v[8:9]
	v_mov_b64_e32 v[22:23], v[6:7]
	v_mov_b64_e32 v[20:21], v[4:5]
	v_mov_b64_e32 v[18:19], v[2:3]
	v_mov_b64_e32 v[16:17], v[0:1]
	v_mov_b64_e32 v[44:45], v[12:13]
	v_mov_b64_e32 v[42:43], v[10:11]
	v_mov_b64_e32 v[40:41], v[8:9]
	v_mov_b64_e32 v[38:39], v[6:7]
	v_mov_b64_e32 v[36:37], v[4:5]
	v_mov_b64_e32 v[34:35], v[2:3]
	v_mov_b64_e32 v[32:33], v[0:1]

; template <int MODE> ...
;     ...
;         const bool more = (s + 2 < T1);
;         if (more) { glds16(kg + (size_t)SU_T(s + 2) * 4096, kdst + s2); glds16(vg + (size_t)SU_T(s + 2) * 4096, vdst + s2); }
.Lk1_noK:
	s_and_b64 vcc, exec, s[24:25]
	s_cbranch_vccnz .Lk1_nodma
	s_add_i32 s4, s12, s20
	s_mov_b32 s5, m0
	s_mov_b32 m0, s4
	s_nop 0
	global_load_lds_dwordx4 v[118:119], off nt
	s_add_i32 s0, s12, s3
	s_mov_b32 m0, s0
	s_nop 0
	global_load_lds_dwordx4 v[116:117], off nt
	s_mov_b32 m0, s5
